# hand-scheduled straight-line FFO residual epilogue for full-mask units: all y_old loads issued ahead of the stores (no store-ack waits), counted vmcnt; on top of v035
# speedup vs baseline: 1.0060x; 1.0036x over previous
.LBB0_736:
	s_cmp_eq_u32 s4, 0
	s_mov_b32 s5, 0x18600000
	s_waitcnt lgkmcnt(0)
	v_readfirstlane_b32 s2, v2
	s_cselect_b32 s5, s5, 0x1aa00000
	s_waitcnt lgkmcnt(0)
	v_readfirstlane_b32 s3, v4
	s_add_u32 s5, s2, s5
	s_addc_u32 s6, s3, 0
	s_lshl_b32 s7, s4, 1
	s_mul_i32 s8, s4, 0x5800000
	s_mul_hi_i32 s7, s7, 0x2c00000
	s_add_u32 s2, s2, s8
	s_addc_u32 s3, s3, s7
	v_readlane_b32 s7, v253, 54
	v_mov_b32_e32 v4, s4
	v_readlane_b32 s4, v253, 56
	v_mov_b32_e32 v2, s7
	v_readlane_b32 s7, v253, 55
	ds_write_b32 v2, v3
	s_add_u32 s2, s2, 0x200000
	v_mov_b32_e32 v2, s7
	ds_write_b32 v2, v4
	v_mov_b32_e32 v2, s4
	v_readlane_b32 s4, v253, 57
	ds_write_b32 v2, v3
	v_mov_b32_e32 v4, 44
	v_mov_b32_e32 v2, s4
	v_readlane_b32 s4, v253, 58
	ds_write_b32 v2, v3
	s_addc_u32 s3, s3, 0
	v_mov_b32_e32 v2, s4
	v_readlane_b32 s4, v253, 59
	ds_write_b32 v2, v233
	s_nop 0
	v_mov_b32_e32 v2, s4
	v_readlane_b32 s4, v253, 60
	ds_write_b32 v2, v4
	v_mov_b32_e32 v4, 0x160
	v_mov_b32_e32 v2, s4
	v_readlane_b32 s4, v253, 61
	ds_write_b32 v2, v235
	s_nop 0
	v_mov_b32_e32 v2, s4
	v_readlane_b32 s4, v253, 62
	ds_write_b32 v2, v4
	v_mov_b32_e32 v4, 32
	v_mov_b32_e32 v2, s4
	v_readlane_b32 s4, v253, 63
	ds_write_b32 v2, v3
	s_nop 0
	v_mov_b32_e32 v2, s4
	v_readlane_b32 s4, v254, 0
	ds_write_b32 v2, v4
	v_mov_b32_e32 v4, s5
	v_mov_b32_e32 v2, s4
	v_readlane_b32 s4, v254, 1
	ds_write_b32 v2, v244
	s_nop 0
	v_mov_b32_e32 v2, s4
	v_readlane_b32 s4, v254, 2
	ds_write_b32 v2, v244
	s_nop 0
	v_mov_b32_e32 v2, s4
	v_readlane_b32 s4, v254, 3
	ds_write_b32 v2, v4
	v_mov_b32_e32 v4, s6
	v_mov_b32_e32 v2, s4
	v_readlane_b32 s4, v254, 4
	ds_write_b32 v2, v4
	v_mov_b32_e32 v4, s2
	v_mov_b32_e32 v2, s4
	v_readlane_b32 s2, v254, 5
	ds_write_b32 v2, v4
	v_mov_b32_e32 v4, s3
	v_mov_b32_e32 v2, s2
	ds_write_b32 v2, v4
	s_branch .LBB0_737

.LBB0_1664:
	s_waitcnt lgkmcnt(0)
	v_readfirstlane_b32 s2, v2
	s_waitcnt lgkmcnt(0)
	v_readfirstlane_b32 s3, v4
	s_add_u32 s5, s2, 0x21600000
	s_addc_u32 s8, s3, 0
	s_lshl_b32 s9, s4, 1
	s_mul_i32 s10, s4, 0x2c00000
	s_mul_hi_i32 s9, s9, 0x1600000
	s_add_u32 s2, s2, s10
	s_addc_u32 s3, s3, s9
	v_readlane_b32 s9, v253, 54
	v_mov_b32_e32 v6, s4
	s_add_u32 s2, s2, 0xb200000
	v_mov_b32_e32 v5, s9
	v_readlane_b32 s9, v253, 55
	ds_write_b32 v5, v193
	s_addc_u32 s3, s3, 0
	v_mov_b32_e32 v5, s9
	v_readlane_b32 s9, v253, 56
	ds_write_b32 v5, v6
	v_mov_b32_e32 v6, 8
	v_mov_b32_e32 v5, s9
	v_readlane_b32 s9, v253, 57
	ds_write_b32 v5, v3
	s_nop 0
	v_mov_b32_e32 v5, s9
	v_readlane_b32 s9, v253, 58
	ds_write_b32 v5, v3
	s_nop 0
	v_mov_b32_e32 v5, s9
	v_readlane_b32 s9, v253, 59
	ds_write_b32 v5, v233
	s_nop 0
	v_mov_b32_e32 v5, s9
	v_readlane_b32 s9, v253, 60
	ds_write_b32 v5, v6
	v_mov_b32_e32 v6, 64
	v_mov_b32_e32 v5, s9
	v_readlane_b32 s9, v253, 61
	ds_write_b32 v5, v235
	s_nop 0
	v_mov_b32_e32 v5, s9
	v_readlane_b32 s9, v253, 62
	ds_write_b32 v5, v6
	v_mov_b32_e32 v6, 0x58
	v_mov_b32_e32 v5, s9
	v_readlane_b32 s9, v253, 63
	ds_write_b32 v5, v3
	s_nop 0
	v_mov_b32_e32 v5, s9
	v_readlane_b32 s9, v254, 0
	ds_write_b32 v5, v6
	v_mov_b32_e32 v6, 0x2c00
	v_mov_b32_e32 v5, s9
	v_readlane_b32 s9, v254, 1
	ds_write_b32 v5, v6
	s_nop 0
	v_mov_b32_e32 v5, s9
	v_readlane_b32 s9, v254, 2
	ds_write_b32 v5, v6
	v_mov_b32_e32 v6, s5
	v_mov_b32_e32 v5, s9
	v_readlane_b32 s5, v254, 3
	ds_write_b32 v5, v6
	v_mov_b32_e32 v6, s8
	v_mov_b32_e32 v5, s5
	v_readlane_b32 s5, v254, 4
	ds_write_b32 v5, v6
	v_mov_b32_e32 v6, s2
	v_mov_b32_e32 v5, s5
	v_readlane_b32 s2, v254, 5
	ds_write_b32 v5, v6
	v_mov_b32_e32 v6, s3
	v_mov_b32_e32 v5, s2
	ds_write_b32 v5, v6
	s_andn2_b64 vcc, exec, s[6:7]
	s_cbranch_vccz .LBB0_736
	s_branch .LBB0_737
.LBB0_737:
	s_or_b64 exec, exec, s[0:1]
	s_and_b32 s2, s83, 7
	s_cmp_eq_u32 s83, 2
	s_cselect_b64 s[0:1], -1, 0
	s_and_b64 s[0:1], s[0:1], exec
	s_movk_i32 s0, 0x654
	s_cselect_b32 s0, s0, 0x120
	s_cmp_eq_u32 s2, 0
	s_cselect_b32 s4, 0x630, s0
	v_readlane_b32 s0, v253, 11
	v_readlane_b32 s1, v253, 12
	s_waitcnt lgkmcnt(0)
	s_barrier
	s_load_dword s9, s[0:1], 0x0
	s_cselect_b32 s5, 4, 8
	s_cmp_eq_u32 s83, 2
	s_cselect_b64 s[0:1], -1, 0
	s_and_b64 s[2:3], s[0:1], exec
	s_cselect_b32 s15, 3, s5
	s_waitcnt lgkmcnt(0)
	s_abs_i32 s2, s9
	v_cvt_f32_u32_e32 v2, s2
	s_sub_i32 s5, 0, s2
	s_ashr_i32 s3, s9, 31
	v_writelane_b32 v255, s9, 13
	v_rcp_iflag_f32_e32 v4, v2
	v_mov_b32_e32 v2, v0
	s_mov_b64 s[12:13], -1
	v_mul_f32_e32 v4, 0x4f7ffffe, v4
	v_cvt_u32_f32_e32 v4, v4
	v_readfirstlane_b32 s16, v2
	v_readfirstlane_b32 s6, v4
	s_mul_i32 s5, s5, s6
	s_mul_hi_u32 s5, s6, s5
	s_add_i32 s6, s6, s5
	s_mul_hi_u32 s5, s4, s6
	s_mul_i32 s6, s5, s2
	s_sub_i32 s6, s4, s6
	s_add_i32 s7, s5, 1
	s_sub_i32 s8, s6, s2
	s_cmp_ge_u32 s6, s2
	s_cselect_b32 s5, s7, s5
	s_cselect_b32 s6, s8, s6
	s_add_i32 s7, s5, 1
	s_cmp_ge_u32 s6, s2
	s_cselect_b32 s2, s7, s5
	s_xor_b32 s2, s2, s3
	s_sub_i32 s3, s2, s3
	s_mul_i32 s2, s3, s9
	s_sub_i32 s14, s4, s2
	v_writelane_b32 v255, s3, 14
	s_cmp_lt_i32 s3, 1
	s_cbranch_scc0 .LBB0_761
	s_mul_i32 s3, s14, s15
	v_readlane_b32 s4, v255, 13
	s_cmp_le_i32 s3, s4
	s_cselect_b32 s5, s15, 1
	v_readlane_b32 s3, v255, 14
	s_cmp_eq_u32 s3, 0
	s_mul_i32 s3, s5, s14
	s_cselect_b64 s[6:7], -1, 0
	s_cmp_lt_i32 s57, s3
	s_cselect_b64 s[8:9], -1, 0
	s_and_b64 s[6:7], s[6:7], s[8:9]
	s_mov_b64 s[12:13], 0
	s_andn2_b64 vcc, exec, s[6:7]
	s_mov_b64 s[6:7], 0
	s_cbranch_vccnz .LBB0_761
	s_abs_i32 s4, s14
	v_cvt_f32_u32_e32 v4, s4
	s_sub_i32 s3, 0, s4
	v_readlane_b32 s7, v253, 22
	s_mov_b32 s75, 0
	v_rcp_iflag_f32_e32 v4, v4
	s_nop 0
	v_mul_f32_e32 v4, 0x4f7ffffe, v4
	v_cvt_u32_f32_e32 v4, v4
	s_nop 0
	v_readfirstlane_b32 s6, v4
	s_mul_i32 s3, s3, s6
	s_mul_hi_u32 s3, s6, s3
	s_add_i32 s6, s6, s3
	s_mul_hi_u32 s3, s7, s6
	s_mul_i32 s6, s3, s4
	s_sub_i32 s10, s7, s6
	s_sub_i32 s11, s10, s4
	s_cmp_ge_u32 s10, s4
	s_cselect_b64 s[6:7], -1, 0
	s_and_b64 s[8:9], s[6:7], exec
	s_cselect_b32 s17, s11, s10
	s_sub_i32 s18, s17, s4
	s_cmp_ge_u32 s17, s4
	s_cselect_b64 s[8:9], -1, 0
	s_and_b64 s[10:11], s[8:9], exec
	s_cselect_b32 s4, s18, s17
	s_xor_b32 s4, s4, s62
	s_sub_i32 s4, s4, s62
	s_andn2_b64 vcc, exec, s[0:1]
	v_writelane_b32 v255, s4, 17
	s_cbranch_vccnz .LBB0_742
	s_add_i32 s4, 0, 0x2144c
	s_mov_b32 s10, 1
	v_readlane_b32 s17, v255, 17

.LBB0_1024:
	s_add_u32 s18, s12, 0x1aa00000
	s_addc_u32 s19, s13, 0
	s_cmp_eq_u32 s84, 0xff
	s_cbranch_scc1 .Lrf_notouch
	v_lshl_add_u32 v138, v191, 3, s70
	v_and_b32_e32 v139, 0x100, v0
	v_lshl_add_u32 v138, s3, 8, v138
	v_lshrrev_b32_e32 v139, 2, v139
	v_add_u32_e32 v139, v139, v189
	v_lshl_add_u32 v139, s4, 8, v139
	v_lshlrev_b32_e32 v139, 12, v139
	v_lshl_add_u32 v139, v138, 1, v139
	global_load_dword v141, v139, s[18:19]
	global_load_dword v141, v139, s[18:19] offset:256
	v_add_u32_e32 v140, 0x10000, v139
	global_load_dword v141, v140, s[18:19]
	global_load_dword v141, v140, s[18:19] offset:256
	v_add_u32_e32 v140, 0x20000, v139
	global_load_dword v141, v140, s[18:19]
	global_load_dword v141, v140, s[18:19] offset:256
	v_add_u32_e32 v140, 0x30000, v139
	global_load_dword v141, v140, s[18:19]
	global_load_dword v141, v140, s[18:19] offset:256
	v_add_u32_e32 v140, 0x80000, v139
	global_load_dword v141, v140, s[18:19]
	global_load_dword v141, v140, s[18:19] offset:256
	v_add_u32_e32 v140, 0x90000, v139
	global_load_dword v141, v140, s[18:19]
	global_load_dword v141, v140, s[18:19] offset:256
	v_add_u32_e32 v140, 0xa0000, v139
	global_load_dword v141, v140, s[18:19]
	global_load_dword v141, v140, s[18:19] offset:256
	v_add_u32_e32 v140, 0xb0000, v139
	global_load_dword v141, v140, s[18:19]
	global_load_dword v141, v140, s[18:19] offset:256
.Lrf_notouch:
	s_mul_hi_i32 s9, s8, 0x12000
	s_mul_i32 s8, s8, 0x12000
	s_add_u32 s8, s12, s8
	s_addc_u32 s9, s13, s9
	s_add_u32 s16, s8, 0x20000
	v_readlane_b32 s8, v254, 38
	s_addc_u32 s17, s9, 0
	s_and_b64 vcc, exec, s[6:7]
	v_mov_b32_e32 v2, s8
	ds_read_b32 v2, v2
	v_readlane_b32 s8, v254, 39
	s_waitcnt lgkmcnt(0)
	s_nop 0
	v_mov_b32_e32 v2, s8
	ds_read_b32 v2, v2
	v_readlane_b32 s8, v254, 40
	s_waitcnt lgkmcnt(0)
	s_nop 0
	v_mov_b32_e32 v2, s8
	ds_read_b32 v2, v2
	v_readlane_b32 s8, v254, 41
	s_waitcnt lgkmcnt(0)
	s_nop 0
	v_mov_b32_e32 v2, s8
	ds_read_b32 v2, v2
	v_readlane_b32 s8, v255, 18
	s_waitcnt lgkmcnt(0)
	v_lshl_add_u32 v2, v191, 3, s70
	v_lshl_add_u32 v178, s3, 8, v2
	v_add_u32_e32 v4, s8, v189
	v_lshl_add_u32 v180, s4, 8, v4
	s_cbranch_vccnz .LBB0_1082
	s_cmp_eq_u32 s84, 0xff
	s_cbranch_scc1 .Lrfast_ffo
	v_ashrrev_i32_e32 v181, 31, v180
	v_lshlrev_b64 v[206:207], 12, v[180:181]
	s_mov_b64 s[0:1], 0x10000
	v_lshl_add_u64 v[212:213], v[206:207], 0, s[0:1]
	s_mov_b64 s[0:1], 0x20000
	v_ashrrev_i32_e32 v179, 31, v178
	v_lshl_add_u64 v[210:211], v[206:207], 0, s[0:1]
	s_mov_b64 s[0:1], 0x30000
	v_lshl_add_u64 v[182:183], v[178:179], 1, s[18:19]
	v_lshl_add_u64 v[208:209], v[206:207], 0, s[0:1]
	v_lshl_add_u64 v[204:205], v[182:183], 0, v[212:213]
	v_lshl_add_u64 v[184:185], v[182:183], 0, v[208:209]
	v_lshl_add_u64 v[186:187], v[182:183], 0, v[210:211]
	global_load_dwordx4 v[170:173], v[204:205], off
	global_load_dwordx4 v[166:169], v[186:187], off
	global_load_dwordx4 v[158:161], v[184:185], off
	v_lshlrev_b32_e32 v4, 3, v4
	v_add_u32_e32 v214, 0, v4
	v_add_u32_e32 v4, 0x20000, v214
	ds_read2_b64 v[174:177], v4 offset1:16
	v_lshl_add_u32 v2, v2, 2, 0
	v_add_u32_e32 v197, 0x20800, v2
	v_add_u32_e32 v199, 0x20c00, v2
	ds_read2_b64 v[162:165], v4 offset0:32 offset1:48
	s_waitcnt lgkmcnt(0)
	v_mul_f32_e32 v201, 0x3a000000, v174
	v_mul_f32_e32 v5, v201, v201
	v_fma_f32 v5, v175, s72, -v5
	v_add_f32_e32 v5, 0x3727c5ac, v5
	s_waitcnt vmcnt(0)
	ds_read_b128 v[150:153], v197
	ds_read_b128 v[142:145], v197 offset:16
	ds_read_b128 v[154:157], v199
	ds_read_b128 v[146:149], v199 offset:16
	v_rsq_f32_e32 v174, v5
	s_and_b32 s6, s84, 1
	s_bitcmp1_b32 s84, 0
	s_cselect_b64 s[0:1], -1, 0
	s_cmp_eq_u32 s6, 0
	s_cbranch_scc1 .LBB0_1048
	v_lshl_add_u64 v[4:5], v[182:183], 0, v[206:207]
	global_load_dwordx4 v[134:137], v[4:5], off
	s_waitcnt vmcnt(0)
	v_lshlrev_b32_e32 v2, 16, v134
	v_and_b32_e32 v4, 0xffff0000, v134
	v_lshlrev_b32_e32 v134, 16, v135
	v_and_b32_e32 v135, 0xffff0000, v135
	v_lshlrev_b32_e32 v175, 16, v136
	v_sub_f32_e32 v5, v4, v201
	v_sub_f32_e32 v4, v2, v201
	v_sub_f32_e32 v135, v135, v201
	v_sub_f32_e32 v134, v134, v201
	v_pk_mul_f32 v[134:135], v[174:175], v[134:135] op_sel_hi:[0,1]
	v_pk_mul_f32 v[4:5], v[174:175], v[4:5] op_sel_hi:[0,1]
	s_waitcnt lgkmcnt(1)
	v_pk_fma_f32 v[4:5], v[150:151], v[4:5], v[154:155]
	v_pk_fma_f32 v[134:135], v[152:153], v[134:135], v[156:157]
	v_and_b32_e32 v136, 0xffff0000, v136
	v_lshlrev_b32_e32 v203, 16, v137
	v_and_b32_e32 v137, 0xffff0000, v137
	v_pk_mul_f32 v[134:135], v[134:135], s[76:77] op_sel_hi:[1,0]
	v_pk_mul_f32 v[4:5], v[4:5], s[76:77] op_sel_hi:[1,0]
	v_pk_fma_f32 v[140:141], v[128:129], 0.5, v[134:135] op_sel_hi:[1,0,1]
	v_pk_fma_f32 v[138:139], v[126:127], 0.5, v[4:5] op_sel_hi:[1,0,1]
	v_sub_f32_e32 v5, v136, v201
	v_sub_f32_e32 v4, v175, v201
	v_sub_f32_e32 v135, v137, v201
	v_sub_f32_e32 v134, v203, v201
	v_pk_mul_f32 v[134:135], v[174:175], v[134:135] op_sel_hi:[0,1]
	v_pk_mul_f32 v[4:5], v[174:175], v[4:5] op_sel_hi:[0,1]
	s_waitcnt lgkmcnt(0)
	v_pk_fma_f32 v[4:5], v[142:143], v[4:5], v[146:147]
	v_pk_fma_f32 v[134:135], v[144:145], v[134:135], v[148:149]
	v_pk_mul_f32 v[4:5], v[4:5], s[76:77] op_sel_hi:[1,0]
	v_pk_mul_f32 v[134:135], v[134:135], s[76:77] op_sel_hi:[1,0]
	v_pk_fma_f32 v[216:217], v[130:131], 0.5, v[4:5] op_sel_hi:[1,0,1]
	v_pk_fma_f32 v[218:219], v[132:133], 0.5, v[134:135] op_sel_hi:[1,0,1]
	v_pk_add_f32 v[134:135], v[138:139], v[216:217]
	v_pk_add_f32 v[4:5], v[140:141], v[218:219]
	v_pk_mul_f32 v[136:137], v[216:217], v[216:217]
	v_pk_mul_f32 v[222:223], v[218:219], v[218:219]
	v_pk_fma_f32 v[136:137], v[138:139], v[138:139], v[136:137]
	v_pk_fma_f32 v[222:223], v[140:141], v[140:141], v[222:223]
	v_pk_mov_b32 v[224:225], v[134:135], v[4:5] op_sel:[1,0]
	v_mov_b32_e32 v135, v5
	v_pk_add_f32 v[4:5], v[224:225], v[134:135]
	v_pk_mov_b32 v[134:135], v[136:137], v[222:223] op_sel:[1,0]
	v_mov_b32_e32 v137, v223
	v_pk_add_f32 v[134:135], v[134:135], v[136:137]
	v_add_f32_e32 v2, v4, v5
	v_pk_add_f32 v[134:135], v[134:135], v[134:135] op_sel:[0,1] op_sel_hi:[1,0]
	v_cvt_pk_bf16_f32 v138, v138, v139
	v_cvt_pk_bf16_f32 v139, v140, v141
	v_cvt_pk_bf16_f32 v140, v216, v217
	v_lshl_add_u64 v[216:217], s[18:19], 0, v[206:207]
	v_add_f32_e32 v2, 0, v2
	v_mov_b32_e32 v4, v3
	v_mov_b32_e32 v5, v3
	v_mov_b32_e32 v135, v3
	v_mov_b32_e32 v136, v3
	v_mov_b32_e32 v137, v3
	v_cvt_pk_bf16_f32 v141, v218, v219
	v_lshl_add_u64 v[216:217], v[178:179], 1, v[216:217]
	global_store_dwordx4 v[216:217], v[138:141], off
	s_branch .LBB0_1049
.Lrfast_ffo:
	v_lshlrev_b32_e32 v134, 12, v180
	v_lshl_add_u32 v134, v178, 1, v134
	v_add_u32_e32 v135, 0x80000, v134
	v_lshl_add_u32 v138, v191, 4, v180
	v_lshlrev_b32_e32 v138, 3, v138
	s_add_u32 s6, s18, 0x10000
	s_addc_u32 s7, s19, 0
	s_add_u32 s8, s18, 0x20000
	s_addc_u32 s9, s19, 0
	s_add_u32 s10, s18, 0x30000
	s_addc_u32 s11, s19, 0
	v_lshlrev_b32_e32 v136, 3, v4
	v_add_u32_e32 v136, 0x20000, v136
	v_lshlrev_b32_e32 v137, 2, v2
	v_add_u32_e32 v137, 0x20800, v137
	global_load_dwordx4 v[204:207], v134, s[18:19]
	global_load_dwordx4 v[208:211], v134, s[6:7]
	global_load_dwordx4 v[212:215], v134, s[8:9]
	global_load_dwordx4 v[216:219], v134, s[10:11]
	global_load_dwordx4 v[222:225], v134, s[18:19] offset:256
	global_load_dwordx4 v[182:185], v134, s[6:7] offset:256
	global_load_dwordx4 v[166:169], v134, s[8:9] offset:256
	global_load_dwordx4 v[170:173], v134, s[10:11] offset:256
	ds_read2_b64 v[142:145], v136 offset0:0 offset1:16
	ds_read2_b64 v[146:149], v136 offset0:32 offset1:48
	ds_read_b128 v[150:153], v137
	ds_read_b128 v[154:157], v137 offset:16
	ds_read_b128 v[158:161], v137 offset:1024
	ds_read_b128 v[162:165], v137 offset:1040
	v_cmp_lt_i32_e32 vcc, v234, v230
	s_nop 1
	v_cndmask_b32_e32 v201, v228, v234, vcc
	v_cmp_lt_i32_e32 vcc, v195, v230
	s_nop 1
	v_cndmask_b32_e32 v203, v228, v195, vcc
	v_lshlrev_b32_e32 v201, 2, v201
	v_lshlrev_b32_e32 v203, 2, v203
	s_waitcnt lgkmcnt(0)
	v_mul_f32_e32 v142, 0x3a000000, v142
	v_mul_f32_e32 v174, v142, v142
	v_fma_f32 v174, v143, s72, -v174
	v_add_f32_e32 v174, 0x3727c5ac, v174
	v_mul_f32_e32 v144, 0x3a000000, v144
	v_mul_f32_e32 v175, v144, v144
	v_fma_f32 v175, v145, s72, -v175
	v_add_f32_e32 v175, 0x3727c5ac, v175
	v_mul_f32_e32 v146, 0x3a000000, v146
	v_mul_f32_e32 v176, v146, v146
	v_fma_f32 v176, v147, s72, -v176
	v_add_f32_e32 v176, 0x3727c5ac, v176
	v_mul_f32_e32 v148, 0x3a000000, v148
	v_mul_f32_e32 v177, v148, v148
	v_fma_f32 v177, v149, s72, -v177
	v_add_f32_e32 v177, 0x3727c5ac, v177
	v_rsq_f32_e32 v143, v174
	v_rsq_f32_e32 v145, v175
	v_rsq_f32_e32 v147, v176
	v_rsq_f32_e32 v149, v177
	s_nop 0
	s_waitcnt vmcnt(4)
	v_lshlrev_b32_e32 v174, 16, v204
	v_and_b32_e32 v175, 0xffff0000, v204
	v_lshlrev_b32_e32 v176, 16, v205
	v_and_b32_e32 v177, 0xffff0000, v205
	v_lshlrev_b32_e32 v178, 16, v206
	v_and_b32_e32 v179, 0xffff0000, v206
	v_lshlrev_b32_e32 v180, 16, v207
	v_and_b32_e32 v181, 0xffff0000, v207
	v_pk_add_f32 v[174:175], v[174:175], v[142:143] op_sel_hi:[1,0] neg_lo:[0,1] neg_hi:[0,1]
	v_pk_add_f32 v[176:177], v[176:177], v[142:143] op_sel_hi:[1,0] neg_lo:[0,1] neg_hi:[0,1]
	v_pk_add_f32 v[178:179], v[178:179], v[142:143] op_sel_hi:[1,0] neg_lo:[0,1] neg_hi:[0,1]
	v_pk_add_f32 v[180:181], v[180:181], v[142:143] op_sel_hi:[1,0] neg_lo:[0,1] neg_hi:[0,1]
	v_pk_mul_f32 v[174:175], v[142:143], v[174:175] op_sel:[1,0] op_sel_hi:[1,1]
	v_pk_mul_f32 v[176:177], v[142:143], v[176:177] op_sel:[1,0] op_sel_hi:[1,1]
	v_pk_mul_f32 v[178:179], v[142:143], v[178:179] op_sel:[1,0] op_sel_hi:[1,1]
	v_pk_mul_f32 v[180:181], v[142:143], v[180:181] op_sel:[1,0] op_sel_hi:[1,1]
	v_pk_fma_f32 v[174:175], v[150:151], v[174:175], v[158:159]
	v_pk_fma_f32 v[176:177], v[152:153], v[176:177], v[160:161]
	v_pk_fma_f32 v[178:179], v[154:155], v[178:179], v[162:163]
	v_pk_fma_f32 v[180:181], v[156:157], v[180:181], v[164:165]
	v_pk_mul_f32 v[174:175], v[174:175], s[76:77] op_sel_hi:[1,0]
	v_pk_mul_f32 v[176:177], v[176:177], s[76:77] op_sel_hi:[1,0]
	v_pk_mul_f32 v[178:179], v[178:179], s[76:77] op_sel_hi:[1,0]
	v_pk_mul_f32 v[180:181], v[180:181], s[76:77] op_sel_hi:[1,0]
	v_pk_fma_f32 v[126:127], v[126:127], 0.5, v[174:175] op_sel_hi:[1,0,1]
	v_pk_fma_f32 v[128:129], v[128:129], 0.5, v[176:177] op_sel_hi:[1,0,1]
	v_pk_fma_f32 v[130:131], v[130:131], 0.5, v[178:179] op_sel_hi:[1,0,1]
	v_pk_fma_f32 v[132:133], v[132:133], 0.5, v[180:181] op_sel_hi:[1,0,1]
	v_pk_add_f32 v[174:175], v[126:127], v[130:131]
	v_pk_add_f32 v[176:177], v[128:129], v[132:133]
	v_pk_mul_f32 v[178:179], v[126:127], v[126:127]
	v_pk_mul_f32 v[180:181], v[128:129], v[128:129]
	v_pk_fma_f32 v[178:179], v[130:131], v[130:131], v[178:179]
	v_pk_fma_f32 v[180:181], v[132:133], v[132:133], v[180:181]
	v_pk_add_f32 v[174:175], v[174:175], v[176:177]
	v_pk_add_f32 v[178:179], v[178:179], v[180:181]
	v_cvt_pk_bf16_f32 v204, v126, v127
	v_cvt_pk_bf16_f32 v205, v128, v129
	v_cvt_pk_bf16_f32 v206, v130, v131
	v_cvt_pk_bf16_f32 v207, v132, v133
	v_add_f32_e32 v2, v174, v175
	v_add_f32_e32 v140, v178, v179
	v_lshlrev_b32_e32 v174, 16, v208
	v_and_b32_e32 v175, 0xffff0000, v208
	v_lshlrev_b32_e32 v176, 16, v209
	v_and_b32_e32 v177, 0xffff0000, v209
	v_lshlrev_b32_e32 v178, 16, v210
	v_and_b32_e32 v179, 0xffff0000, v210
	v_lshlrev_b32_e32 v180, 16, v211
	v_and_b32_e32 v181, 0xffff0000, v211
	v_pk_add_f32 v[174:175], v[174:175], v[144:145] op_sel_hi:[1,0] neg_lo:[0,1] neg_hi:[0,1]
	v_pk_add_f32 v[176:177], v[176:177], v[144:145] op_sel_hi:[1,0] neg_lo:[0,1] neg_hi:[0,1]
	v_pk_add_f32 v[178:179], v[178:179], v[144:145] op_sel_hi:[1,0] neg_lo:[0,1] neg_hi:[0,1]
	v_pk_add_f32 v[180:181], v[180:181], v[144:145] op_sel_hi:[1,0] neg_lo:[0,1] neg_hi:[0,1]
	v_pk_mul_f32 v[174:175], v[144:145], v[174:175] op_sel:[1,0] op_sel_hi:[1,1]
	v_pk_mul_f32 v[176:177], v[144:145], v[176:177] op_sel:[1,0] op_sel_hi:[1,1]
	v_pk_mul_f32 v[178:179], v[144:145], v[178:179] op_sel:[1,0] op_sel_hi:[1,1]
	v_pk_mul_f32 v[180:181], v[144:145], v[180:181] op_sel:[1,0] op_sel_hi:[1,1]
	v_pk_fma_f32 v[174:175], v[150:151], v[174:175], v[158:159]
	v_pk_fma_f32 v[176:177], v[152:153], v[176:177], v[160:161]
	v_pk_fma_f32 v[178:179], v[154:155], v[178:179], v[162:163]
	v_pk_fma_f32 v[180:181], v[156:157], v[180:181], v[164:165]
	v_pk_mul_f32 v[174:175], v[174:175], s[76:77] op_sel_hi:[1,0]
	v_pk_mul_f32 v[176:177], v[176:177], s[76:77] op_sel_hi:[1,0]
	v_pk_mul_f32 v[178:179], v[178:179], s[76:77] op_sel_hi:[1,0]
	v_pk_mul_f32 v[180:181], v[180:181], s[76:77] op_sel_hi:[1,0]
	v_pk_fma_f32 v[118:119], v[118:119], 0.5, v[174:175] op_sel_hi:[1,0,1]
	v_pk_fma_f32 v[120:121], v[120:121], 0.5, v[176:177] op_sel_hi:[1,0,1]
	v_pk_fma_f32 v[122:123], v[122:123], 0.5, v[178:179] op_sel_hi:[1,0,1]
	v_pk_fma_f32 v[124:125], v[124:125], 0.5, v[180:181] op_sel_hi:[1,0,1]
	v_pk_add_f32 v[174:175], v[118:119], v[122:123]
	v_pk_add_f32 v[176:177], v[120:121], v[124:125]
	v_pk_mul_f32 v[178:179], v[118:119], v[118:119]
	v_pk_mul_f32 v[180:181], v[120:121], v[120:121]
	v_pk_fma_f32 v[178:179], v[122:123], v[122:123], v[178:179]
	v_pk_fma_f32 v[180:181], v[124:125], v[124:125], v[180:181]
	v_pk_add_f32 v[174:175], v[174:175], v[176:177]
	v_pk_add_f32 v[178:179], v[178:179], v[180:181]
	v_cvt_pk_bf16_f32 v208, v118, v119
	v_cvt_pk_bf16_f32 v209, v120, v121
	v_cvt_pk_bf16_f32 v210, v122, v123
	v_cvt_pk_bf16_f32 v211, v124, v125
	v_add_f32_e32 v4, v174, v175
	v_add_f32_e32 v186, v178, v179
	v_lshlrev_b32_e32 v174, 16, v212
	v_and_b32_e32 v175, 0xffff0000, v212
	v_lshlrev_b32_e32 v176, 16, v213
	v_and_b32_e32 v177, 0xffff0000, v213
	v_lshlrev_b32_e32 v178, 16, v214
	v_and_b32_e32 v179, 0xffff0000, v214
	v_lshlrev_b32_e32 v180, 16, v215
	v_and_b32_e32 v181, 0xffff0000, v215
	v_pk_add_f32 v[174:175], v[174:175], v[146:147] op_sel_hi:[1,0] neg_lo:[0,1] neg_hi:[0,1]
	v_pk_add_f32 v[176:177], v[176:177], v[146:147] op_sel_hi:[1,0] neg_lo:[0,1] neg_hi:[0,1]
	v_pk_add_f32 v[178:179], v[178:179], v[146:147] op_sel_hi:[1,0] neg_lo:[0,1] neg_hi:[0,1]
	v_pk_add_f32 v[180:181], v[180:181], v[146:147] op_sel_hi:[1,0] neg_lo:[0,1] neg_hi:[0,1]
	v_pk_mul_f32 v[174:175], v[146:147], v[174:175] op_sel:[1,0] op_sel_hi:[1,1]
	v_pk_mul_f32 v[176:177], v[146:147], v[176:177] op_sel:[1,0] op_sel_hi:[1,1]
	v_pk_mul_f32 v[178:179], v[146:147], v[178:179] op_sel:[1,0] op_sel_hi:[1,1]
	v_pk_mul_f32 v[180:181], v[146:147], v[180:181] op_sel:[1,0] op_sel_hi:[1,1]
	v_pk_fma_f32 v[174:175], v[150:151], v[174:175], v[158:159]
	v_pk_fma_f32 v[176:177], v[152:153], v[176:177], v[160:161]
	v_pk_fma_f32 v[178:179], v[154:155], v[178:179], v[162:163]
	v_pk_fma_f32 v[180:181], v[156:157], v[180:181], v[164:165]
	v_pk_mul_f32 v[174:175], v[174:175], s[76:77] op_sel_hi:[1,0]
	v_pk_mul_f32 v[176:177], v[176:177], s[76:77] op_sel_hi:[1,0]
	v_pk_mul_f32 v[178:179], v[178:179], s[76:77] op_sel_hi:[1,0]
	v_pk_mul_f32 v[180:181], v[180:181], s[76:77] op_sel_hi:[1,0]
	v_pk_fma_f32 v[110:111], v[110:111], 0.5, v[174:175] op_sel_hi:[1,0,1]
	v_pk_fma_f32 v[112:113], v[112:113], 0.5, v[176:177] op_sel_hi:[1,0,1]
	v_pk_fma_f32 v[114:115], v[114:115], 0.5, v[178:179] op_sel_hi:[1,0,1]
	v_pk_fma_f32 v[116:117], v[116:117], 0.5, v[180:181] op_sel_hi:[1,0,1]
	v_pk_add_f32 v[174:175], v[110:111], v[114:115]
	v_pk_add_f32 v[176:177], v[112:113], v[116:117]
	v_pk_mul_f32 v[178:179], v[110:111], v[110:111]
	v_pk_mul_f32 v[180:181], v[112:113], v[112:113]
	v_pk_fma_f32 v[178:179], v[114:115], v[114:115], v[178:179]
	v_pk_fma_f32 v[180:181], v[116:117], v[116:117], v[180:181]
	v_pk_add_f32 v[174:175], v[174:175], v[176:177]
	v_pk_add_f32 v[178:179], v[178:179], v[180:181]
	v_cvt_pk_bf16_f32 v212, v110, v111
	v_cvt_pk_bf16_f32 v213, v112, v113
	v_cvt_pk_bf16_f32 v214, v114, v115
	v_cvt_pk_bf16_f32 v215, v116, v117
	v_add_f32_e32 v5, v174, v175
	v_add_f32_e32 v187, v178, v179
	v_lshlrev_b32_e32 v174, 16, v216
	v_and_b32_e32 v175, 0xffff0000, v216
	v_lshlrev_b32_e32 v176, 16, v217
	v_and_b32_e32 v177, 0xffff0000, v217
	v_lshlrev_b32_e32 v178, 16, v218
	v_and_b32_e32 v179, 0xffff0000, v218
	v_lshlrev_b32_e32 v180, 16, v219
	v_and_b32_e32 v181, 0xffff0000, v219
	v_pk_add_f32 v[174:175], v[174:175], v[148:149] op_sel_hi:[1,0] neg_lo:[0,1] neg_hi:[0,1]
	v_pk_add_f32 v[176:177], v[176:177], v[148:149] op_sel_hi:[1,0] neg_lo:[0,1] neg_hi:[0,1]
	v_pk_add_f32 v[178:179], v[178:179], v[148:149] op_sel_hi:[1,0] neg_lo:[0,1] neg_hi:[0,1]
	v_pk_add_f32 v[180:181], v[180:181], v[148:149] op_sel_hi:[1,0] neg_lo:[0,1] neg_hi:[0,1]
	v_pk_mul_f32 v[174:175], v[148:149], v[174:175] op_sel:[1,0] op_sel_hi:[1,1]
	v_pk_mul_f32 v[176:177], v[148:149], v[176:177] op_sel:[1,0] op_sel_hi:[1,1]
	v_pk_mul_f32 v[178:179], v[148:149], v[178:179] op_sel:[1,0] op_sel_hi:[1,1]
	v_pk_mul_f32 v[180:181], v[148:149], v[180:181] op_sel:[1,0] op_sel_hi:[1,1]
	v_pk_fma_f32 v[174:175], v[150:151], v[174:175], v[158:159]
	v_pk_fma_f32 v[176:177], v[152:153], v[176:177], v[160:161]
	v_pk_fma_f32 v[178:179], v[154:155], v[178:179], v[162:163]
	v_pk_fma_f32 v[180:181], v[156:157], v[180:181], v[164:165]
	v_pk_mul_f32 v[174:175], v[174:175], s[76:77] op_sel_hi:[1,0]
	v_pk_mul_f32 v[176:177], v[176:177], s[76:77] op_sel_hi:[1,0]
	v_pk_mul_f32 v[178:179], v[178:179], s[76:77] op_sel_hi:[1,0]
	v_pk_mul_f32 v[180:181], v[180:181], s[76:77] op_sel_hi:[1,0]
	v_pk_fma_f32 v[102:103], v[102:103], 0.5, v[174:175] op_sel_hi:[1,0,1]
	v_pk_fma_f32 v[104:105], v[104:105], 0.5, v[176:177] op_sel_hi:[1,0,1]
	v_pk_fma_f32 v[106:107], v[106:107], 0.5, v[178:179] op_sel_hi:[1,0,1]
	v_pk_fma_f32 v[108:109], v[108:109], 0.5, v[180:181] op_sel_hi:[1,0,1]
	v_pk_add_f32 v[174:175], v[102:103], v[106:107]
	v_pk_add_f32 v[176:177], v[104:105], v[108:109]
	v_pk_mul_f32 v[178:179], v[102:103], v[102:103]
	v_pk_mul_f32 v[180:181], v[104:105], v[104:105]
	v_pk_fma_f32 v[178:179], v[106:107], v[106:107], v[178:179]
	v_pk_fma_f32 v[180:181], v[108:109], v[108:109], v[180:181]
	v_pk_add_f32 v[174:175], v[174:175], v[176:177]
	v_pk_add_f32 v[178:179], v[178:179], v[180:181]
	v_cvt_pk_bf16_f32 v216, v102, v103
	v_cvt_pk_bf16_f32 v217, v104, v105
	v_cvt_pk_bf16_f32 v218, v106, v107
	v_cvt_pk_bf16_f32 v219, v108, v109
	v_add_f32_e32 v139, v174, v175
	v_add_f32_e32 v197, v178, v179
	global_load_dwordx4 v[102:105], v135, s[18:19]
	global_load_dwordx4 v[106:109], v135, s[6:7]
	global_load_dwordx4 v[110:113], v135, s[8:9]
	global_load_dwordx4 v[114:117], v135, s[10:11]
	global_load_dwordx4 v[118:121], v135, s[18:19] offset:256
	global_load_dwordx4 v[122:125], v135, s[6:7] offset:256
	global_load_dwordx4 v[126:129], v135, s[8:9] offset:256
	global_load_dwordx4 v[130:133], v135, s[10:11] offset:256
	global_store_dwordx4 v134, v[204:207], s[18:19]
	global_store_dwordx4 v134, v[208:211], s[6:7]
	global_store_dwordx4 v134, v[212:215], s[8:9]
	global_store_dwordx4 v134, v[216:219], s[10:11]
	ds_read_b128 v[150:153], v137 offset:512
	ds_read_b128 v[154:157], v137 offset:528
	ds_read_b128 v[158:161], v137 offset:1536
	ds_read_b128 v[162:165], v137 offset:1552
	s_waitcnt lgkmcnt(0)
	s_waitcnt vmcnt(12)
	v_lshlrev_b32_e32 v174, 16, v222
	v_and_b32_e32 v175, 0xffff0000, v222
	v_lshlrev_b32_e32 v176, 16, v223
	v_and_b32_e32 v177, 0xffff0000, v223
	v_lshlrev_b32_e32 v178, 16, v224
	v_and_b32_e32 v179, 0xffff0000, v224
	v_lshlrev_b32_e32 v180, 16, v225
	v_and_b32_e32 v181, 0xffff0000, v225
	v_pk_add_f32 v[174:175], v[174:175], v[142:143] op_sel_hi:[1,0] neg_lo:[0,1] neg_hi:[0,1]
	v_pk_add_f32 v[176:177], v[176:177], v[142:143] op_sel_hi:[1,0] neg_lo:[0,1] neg_hi:[0,1]
	v_pk_add_f32 v[178:179], v[178:179], v[142:143] op_sel_hi:[1,0] neg_lo:[0,1] neg_hi:[0,1]
	v_pk_add_f32 v[180:181], v[180:181], v[142:143] op_sel_hi:[1,0] neg_lo:[0,1] neg_hi:[0,1]
	v_pk_mul_f32 v[174:175], v[142:143], v[174:175] op_sel:[1,0] op_sel_hi:[1,1]
	v_pk_mul_f32 v[176:177], v[142:143], v[176:177] op_sel:[1,0] op_sel_hi:[1,1]
	v_pk_mul_f32 v[178:179], v[142:143], v[178:179] op_sel:[1,0] op_sel_hi:[1,1]
	v_pk_mul_f32 v[180:181], v[142:143], v[180:181] op_sel:[1,0] op_sel_hi:[1,1]
	v_pk_fma_f32 v[174:175], v[150:151], v[174:175], v[158:159]
	v_pk_fma_f32 v[176:177], v[152:153], v[176:177], v[160:161]
	v_pk_fma_f32 v[178:179], v[154:155], v[178:179], v[162:163]
	v_pk_fma_f32 v[180:181], v[156:157], v[180:181], v[164:165]
	v_pk_mul_f32 v[174:175], v[174:175], s[76:77] op_sel_hi:[1,0]
	v_pk_mul_f32 v[176:177], v[176:177], s[76:77] op_sel_hi:[1,0]
	v_pk_mul_f32 v[178:179], v[178:179], s[76:77] op_sel_hi:[1,0]
	v_pk_mul_f32 v[180:181], v[180:181], s[76:77] op_sel_hi:[1,0]
	v_pk_fma_f32 v[94:95], v[94:95], 0.5, v[174:175] op_sel_hi:[1,0,1]
	v_pk_fma_f32 v[96:97], v[96:97], 0.5, v[176:177] op_sel_hi:[1,0,1]
	v_pk_fma_f32 v[98:99], v[98:99], 0.5, v[178:179] op_sel_hi:[1,0,1]
	v_pk_fma_f32 v[100:101], v[100:101], 0.5, v[180:181] op_sel_hi:[1,0,1]
	v_pk_add_f32 v[174:175], v[94:95], v[98:99]
	v_pk_add_f32 v[176:177], v[96:97], v[100:101]
	v_pk_mul_f32 v[178:179], v[94:95], v[94:95]
	v_pk_mul_f32 v[180:181], v[96:97], v[96:97]
	v_pk_fma_f32 v[178:179], v[98:99], v[98:99], v[178:179]
	v_pk_fma_f32 v[180:181], v[100:101], v[100:101], v[180:181]
	v_pk_add_f32 v[174:175], v[174:175], v[176:177]
	v_pk_add_f32 v[178:179], v[178:179], v[180:181]
	v_cvt_pk_bf16_f32 v222, v94, v95
	v_cvt_pk_bf16_f32 v223, v96, v97
	v_cvt_pk_bf16_f32 v224, v98, v99
	v_cvt_pk_bf16_f32 v225, v100, v101
	v_add_f32_e32 v174, v174, v175
	v_add_f32_e32 v178, v178, v179
	v_add_f32_e32 v2, v2, v174
	v_add_f32_e32 v140, v140, v178
	v_lshlrev_b32_e32 v174, 16, v182
	v_and_b32_e32 v175, 0xffff0000, v182
	v_lshlrev_b32_e32 v176, 16, v183
	v_and_b32_e32 v177, 0xffff0000, v183
	v_lshlrev_b32_e32 v178, 16, v184
	v_and_b32_e32 v179, 0xffff0000, v184
	v_lshlrev_b32_e32 v180, 16, v185
	v_and_b32_e32 v181, 0xffff0000, v185
	v_pk_add_f32 v[174:175], v[174:175], v[144:145] op_sel_hi:[1,0] neg_lo:[0,1] neg_hi:[0,1]
	v_pk_add_f32 v[176:177], v[176:177], v[144:145] op_sel_hi:[1,0] neg_lo:[0,1] neg_hi:[0,1]
	v_pk_add_f32 v[178:179], v[178:179], v[144:145] op_sel_hi:[1,0] neg_lo:[0,1] neg_hi:[0,1]
	v_pk_add_f32 v[180:181], v[180:181], v[144:145] op_sel_hi:[1,0] neg_lo:[0,1] neg_hi:[0,1]
	v_pk_mul_f32 v[174:175], v[144:145], v[174:175] op_sel:[1,0] op_sel_hi:[1,1]
	v_pk_mul_f32 v[176:177], v[144:145], v[176:177] op_sel:[1,0] op_sel_hi:[1,1]
	v_pk_mul_f32 v[178:179], v[144:145], v[178:179] op_sel:[1,0] op_sel_hi:[1,1]
	v_pk_mul_f32 v[180:181], v[144:145], v[180:181] op_sel:[1,0] op_sel_hi:[1,1]
	v_pk_fma_f32 v[174:175], v[150:151], v[174:175], v[158:159]
	v_pk_fma_f32 v[176:177], v[152:153], v[176:177], v[160:161]
	v_pk_fma_f32 v[178:179], v[154:155], v[178:179], v[162:163]
	v_pk_fma_f32 v[180:181], v[156:157], v[180:181], v[164:165]
	v_pk_mul_f32 v[174:175], v[174:175], s[76:77] op_sel_hi:[1,0]
	v_pk_mul_f32 v[176:177], v[176:177], s[76:77] op_sel_hi:[1,0]
	v_pk_mul_f32 v[178:179], v[178:179], s[76:77] op_sel_hi:[1,0]
	v_pk_mul_f32 v[180:181], v[180:181], s[76:77] op_sel_hi:[1,0]
	v_pk_fma_f32 v[86:87], v[86:87], 0.5, v[174:175] op_sel_hi:[1,0,1]
	v_pk_fma_f32 v[88:89], v[88:89], 0.5, v[176:177] op_sel_hi:[1,0,1]
	v_pk_fma_f32 v[90:91], v[90:91], 0.5, v[178:179] op_sel_hi:[1,0,1]
	v_pk_fma_f32 v[92:93], v[92:93], 0.5, v[180:181] op_sel_hi:[1,0,1]
	v_pk_add_f32 v[174:175], v[86:87], v[90:91]
	v_pk_add_f32 v[176:177], v[88:89], v[92:93]
	v_pk_mul_f32 v[178:179], v[86:87], v[86:87]
	v_pk_mul_f32 v[180:181], v[88:89], v[88:89]
	v_pk_fma_f32 v[178:179], v[90:91], v[90:91], v[178:179]
	v_pk_fma_f32 v[180:181], v[92:93], v[92:93], v[180:181]
	v_pk_add_f32 v[174:175], v[174:175], v[176:177]
	v_pk_add_f32 v[178:179], v[178:179], v[180:181]
	v_cvt_pk_bf16_f32 v182, v86, v87
	v_cvt_pk_bf16_f32 v183, v88, v89
	v_cvt_pk_bf16_f32 v184, v90, v91
	v_cvt_pk_bf16_f32 v185, v92, v93
	v_add_f32_e32 v174, v174, v175
	v_add_f32_e32 v178, v178, v179
	v_add_f32_e32 v4, v4, v174
	v_add_f32_e32 v186, v186, v178
	v_lshlrev_b32_e32 v174, 16, v166
	v_and_b32_e32 v175, 0xffff0000, v166
	v_lshlrev_b32_e32 v176, 16, v167
	v_and_b32_e32 v177, 0xffff0000, v167
	v_lshlrev_b32_e32 v178, 16, v168
	v_and_b32_e32 v179, 0xffff0000, v168
	v_lshlrev_b32_e32 v180, 16, v169
	v_and_b32_e32 v181, 0xffff0000, v169
	v_pk_add_f32 v[174:175], v[174:175], v[146:147] op_sel_hi:[1,0] neg_lo:[0,1] neg_hi:[0,1]
	v_pk_add_f32 v[176:177], v[176:177], v[146:147] op_sel_hi:[1,0] neg_lo:[0,1] neg_hi:[0,1]
	v_pk_add_f32 v[178:179], v[178:179], v[146:147] op_sel_hi:[1,0] neg_lo:[0,1] neg_hi:[0,1]
	v_pk_add_f32 v[180:181], v[180:181], v[146:147] op_sel_hi:[1,0] neg_lo:[0,1] neg_hi:[0,1]
	v_pk_mul_f32 v[174:175], v[146:147], v[174:175] op_sel:[1,0] op_sel_hi:[1,1]
	v_pk_mul_f32 v[176:177], v[146:147], v[176:177] op_sel:[1,0] op_sel_hi:[1,1]
	v_pk_mul_f32 v[178:179], v[146:147], v[178:179] op_sel:[1,0] op_sel_hi:[1,1]
	v_pk_mul_f32 v[180:181], v[146:147], v[180:181] op_sel:[1,0] op_sel_hi:[1,1]
	v_pk_fma_f32 v[174:175], v[150:151], v[174:175], v[158:159]
	v_pk_fma_f32 v[176:177], v[152:153], v[176:177], v[160:161]
	v_pk_fma_f32 v[178:179], v[154:155], v[178:179], v[162:163]
	v_pk_fma_f32 v[180:181], v[156:157], v[180:181], v[164:165]
	v_pk_mul_f32 v[174:175], v[174:175], s[76:77] op_sel_hi:[1,0]
	v_pk_mul_f32 v[176:177], v[176:177], s[76:77] op_sel_hi:[1,0]
	v_pk_mul_f32 v[178:179], v[178:179], s[76:77] op_sel_hi:[1,0]
	v_pk_mul_f32 v[180:181], v[180:181], s[76:77] op_sel_hi:[1,0]
	v_pk_fma_f32 v[78:79], v[78:79], 0.5, v[174:175] op_sel_hi:[1,0,1]
	v_pk_fma_f32 v[80:81], v[80:81], 0.5, v[176:177] op_sel_hi:[1,0,1]
	v_pk_fma_f32 v[82:83], v[82:83], 0.5, v[178:179] op_sel_hi:[1,0,1]
	v_pk_fma_f32 v[84:85], v[84:85], 0.5, v[180:181] op_sel_hi:[1,0,1]
	v_pk_add_f32 v[174:175], v[78:79], v[82:83]
	v_pk_add_f32 v[176:177], v[80:81], v[84:85]
	v_pk_mul_f32 v[178:179], v[78:79], v[78:79]
	v_pk_mul_f32 v[180:181], v[80:81], v[80:81]
	v_pk_fma_f32 v[178:179], v[82:83], v[82:83], v[178:179]
	v_pk_fma_f32 v[180:181], v[84:85], v[84:85], v[180:181]
	v_pk_add_f32 v[174:175], v[174:175], v[176:177]
	v_pk_add_f32 v[178:179], v[178:179], v[180:181]
	v_cvt_pk_bf16_f32 v166, v78, v79
	v_cvt_pk_bf16_f32 v167, v80, v81
	v_cvt_pk_bf16_f32 v168, v82, v83
	v_cvt_pk_bf16_f32 v169, v84, v85
	v_add_f32_e32 v174, v174, v175
	v_add_f32_e32 v178, v178, v179
	v_add_f32_e32 v5, v5, v174
	v_add_f32_e32 v187, v187, v178
	v_lshlrev_b32_e32 v174, 16, v170
	v_and_b32_e32 v175, 0xffff0000, v170
	v_lshlrev_b32_e32 v176, 16, v171
	v_and_b32_e32 v177, 0xffff0000, v171
	v_lshlrev_b32_e32 v178, 16, v172
	v_and_b32_e32 v179, 0xffff0000, v172
	v_lshlrev_b32_e32 v180, 16, v173
	v_and_b32_e32 v181, 0xffff0000, v173
	v_pk_add_f32 v[174:175], v[174:175], v[148:149] op_sel_hi:[1,0] neg_lo:[0,1] neg_hi:[0,1]
	v_pk_add_f32 v[176:177], v[176:177], v[148:149] op_sel_hi:[1,0] neg_lo:[0,1] neg_hi:[0,1]
	v_pk_add_f32 v[178:179], v[178:179], v[148:149] op_sel_hi:[1,0] neg_lo:[0,1] neg_hi:[0,1]
	v_pk_add_f32 v[180:181], v[180:181], v[148:149] op_sel_hi:[1,0] neg_lo:[0,1] neg_hi:[0,1]
	v_pk_mul_f32 v[174:175], v[148:149], v[174:175] op_sel:[1,0] op_sel_hi:[1,1]
	v_pk_mul_f32 v[176:177], v[148:149], v[176:177] op_sel:[1,0] op_sel_hi:[1,1]
	v_pk_mul_f32 v[178:179], v[148:149], v[178:179] op_sel:[1,0] op_sel_hi:[1,1]
	v_pk_mul_f32 v[180:181], v[148:149], v[180:181] op_sel:[1,0] op_sel_hi:[1,1]
	v_pk_fma_f32 v[174:175], v[150:151], v[174:175], v[158:159]
	v_pk_fma_f32 v[176:177], v[152:153], v[176:177], v[160:161]
	v_pk_fma_f32 v[178:179], v[154:155], v[178:179], v[162:163]
	v_pk_fma_f32 v[180:181], v[156:157], v[180:181], v[164:165]
	v_pk_mul_f32 v[174:175], v[174:175], s[76:77] op_sel_hi:[1,0]
	v_pk_mul_f32 v[176:177], v[176:177], s[76:77] op_sel_hi:[1,0]
	v_pk_mul_f32 v[178:179], v[178:179], s[76:77] op_sel_hi:[1,0]
	v_pk_mul_f32 v[180:181], v[180:181], s[76:77] op_sel_hi:[1,0]
	v_pk_fma_f32 v[70:71], v[70:71], 0.5, v[174:175] op_sel_hi:[1,0,1]
	v_pk_fma_f32 v[72:73], v[72:73], 0.5, v[176:177] op_sel_hi:[1,0,1]
	v_pk_fma_f32 v[74:75], v[74:75], 0.5, v[178:179] op_sel_hi:[1,0,1]
	v_pk_fma_f32 v[76:77], v[76:77], 0.5, v[180:181] op_sel_hi:[1,0,1]
	v_pk_add_f32 v[174:175], v[70:71], v[74:75]
	v_pk_add_f32 v[176:177], v[72:73], v[76:77]
	v_pk_mul_f32 v[178:179], v[70:71], v[70:71]
	v_pk_mul_f32 v[180:181], v[72:73], v[72:73]
	v_pk_fma_f32 v[178:179], v[74:75], v[74:75], v[178:179]
	v_pk_fma_f32 v[180:181], v[76:77], v[76:77], v[180:181]
	v_pk_add_f32 v[174:175], v[174:175], v[176:177]
	v_pk_add_f32 v[178:179], v[178:179], v[180:181]
	v_cvt_pk_bf16_f32 v170, v70, v71
	v_cvt_pk_bf16_f32 v171, v72, v73
	v_cvt_pk_bf16_f32 v172, v74, v75
	v_cvt_pk_bf16_f32 v173, v76, v77
	v_add_f32_e32 v174, v174, v175
	v_add_f32_e32 v178, v178, v179
	v_add_f32_e32 v139, v139, v174
	v_add_f32_e32 v197, v197, v178
	global_store_dwordx4 v134, v[222:225], s[18:19] offset:256
	global_store_dwordx4 v134, v[182:185], s[6:7] offset:256
	global_store_dwordx4 v134, v[166:169], s[8:9] offset:256
	global_store_dwordx4 v134, v[170:173], s[10:11] offset:256
	ds_bpermute_b32 v174, v201, v2
	ds_bpermute_b32 v175, v201, v4
	ds_bpermute_b32 v176, v201, v5
	ds_bpermute_b32 v177, v201, v139
	ds_bpermute_b32 v178, v201, v140
	ds_bpermute_b32 v179, v201, v186
	ds_bpermute_b32 v180, v201, v187
	ds_bpermute_b32 v181, v201, v197
	s_waitcnt lgkmcnt(0)
	v_add_f32_e32 v2, v2, v174
	v_add_f32_e32 v4, v4, v175
	v_add_f32_e32 v5, v5, v176
	v_add_f32_e32 v139, v139, v177
	v_add_f32_e32 v140, v140, v178
	v_add_f32_e32 v186, v186, v179
	v_add_f32_e32 v187, v187, v180
	v_add_f32_e32 v197, v197, v181
	ds_bpermute_b32 v174, v203, v2
	ds_bpermute_b32 v175, v203, v4
	ds_bpermute_b32 v176, v203, v5
	ds_bpermute_b32 v177, v203, v139
	ds_bpermute_b32 v178, v203, v140
	ds_bpermute_b32 v179, v203, v186
	ds_bpermute_b32 v180, v203, v187
	ds_bpermute_b32 v181, v203, v197
	s_waitcnt lgkmcnt(0)
	v_add_f32_e32 v2, v2, v174
	v_add_f32_e32 v4, v4, v175
	v_add_f32_e32 v5, v5, v176
	v_add_f32_e32 v139, v139, v177
	v_add_f32_e32 v140, v140, v178
	v_add_f32_e32 v186, v186, v179
	v_add_f32_e32 v187, v187, v180
	v_add_f32_e32 v197, v197, v181
	v_cmp_eq_u32_e32 vcc, 1, v191
	s_nop 1
	v_cndmask_b32_e32 v2, v2, v4, vcc
	v_cndmask_b32_e32 v140, v140, v186, vcc
	v_cmp_eq_u32_e32 vcc, 2, v191
	s_nop 1
	v_cndmask_b32_e32 v2, v2, v5, vcc
	v_cndmask_b32_e32 v140, v140, v187, vcc
	v_cmp_eq_u32_e32 vcc, 3, v191
	s_nop 1
	v_cndmask_b32_e32 v2, v2, v139, vcc
	v_cndmask_b32_e32 v140, v140, v197, vcc
	global_atomic_add_f32 v138, v2, s[16:17]
	global_atomic_add_f32 v138, v140, s[16:17] offset:4
	ds_read2_b64 v[142:145], v136 offset0:128 offset1:144
	ds_read2_b64 v[146:149], v136 offset0:160 offset1:176
	ds_read_b128 v[150:153], v137
	ds_read_b128 v[154:157], v137 offset:16
	ds_read_b128 v[158:161], v137 offset:1024
	ds_read_b128 v[162:165], v137 offset:1040
	s_waitcnt lgkmcnt(0)
	v_mul_f32_e32 v142, 0x3a000000, v142
	v_mul_f32_e32 v174, v142, v142
	v_fma_f32 v174, v143, s72, -v174
	v_add_f32_e32 v174, 0x3727c5ac, v174
	v_mul_f32_e32 v144, 0x3a000000, v144
	v_mul_f32_e32 v175, v144, v144
	v_fma_f32 v175, v145, s72, -v175
	v_add_f32_e32 v175, 0x3727c5ac, v175
	v_mul_f32_e32 v146, 0x3a000000, v146
	v_mul_f32_e32 v176, v146, v146
	v_fma_f32 v176, v147, s72, -v176
	v_add_f32_e32 v176, 0x3727c5ac, v176
	v_mul_f32_e32 v148, 0x3a000000, v148
	v_mul_f32_e32 v177, v148, v148
	v_fma_f32 v177, v149, s72, -v177
	v_add_f32_e32 v177, 0x3727c5ac, v177
	v_rsq_f32_e32 v143, v174
	v_rsq_f32_e32 v145, v175
	v_rsq_f32_e32 v147, v176
	v_rsq_f32_e32 v149, v177
	s_nop 0
	s_waitcnt vmcnt(14)
	v_lshlrev_b32_e32 v174, 16, v102
	v_and_b32_e32 v175, 0xffff0000, v102
	v_lshlrev_b32_e32 v176, 16, v103
	v_and_b32_e32 v177, 0xffff0000, v103
	v_lshlrev_b32_e32 v178, 16, v104
	v_and_b32_e32 v179, 0xffff0000, v104
	v_lshlrev_b32_e32 v180, 16, v105
	v_and_b32_e32 v181, 0xffff0000, v105
	v_pk_add_f32 v[174:175], v[174:175], v[142:143] op_sel_hi:[1,0] neg_lo:[0,1] neg_hi:[0,1]
	v_pk_add_f32 v[176:177], v[176:177], v[142:143] op_sel_hi:[1,0] neg_lo:[0,1] neg_hi:[0,1]
	v_pk_add_f32 v[178:179], v[178:179], v[142:143] op_sel_hi:[1,0] neg_lo:[0,1] neg_hi:[0,1]
	v_pk_add_f32 v[180:181], v[180:181], v[142:143] op_sel_hi:[1,0] neg_lo:[0,1] neg_hi:[0,1]
	v_pk_mul_f32 v[174:175], v[142:143], v[174:175] op_sel:[1,0] op_sel_hi:[1,1]
	v_pk_mul_f32 v[176:177], v[142:143], v[176:177] op_sel:[1,0] op_sel_hi:[1,1]
	v_pk_mul_f32 v[178:179], v[142:143], v[178:179] op_sel:[1,0] op_sel_hi:[1,1]
	v_pk_mul_f32 v[180:181], v[142:143], v[180:181] op_sel:[1,0] op_sel_hi:[1,1]
	v_pk_fma_f32 v[174:175], v[150:151], v[174:175], v[158:159]
	v_pk_fma_f32 v[176:177], v[152:153], v[176:177], v[160:161]
	v_pk_fma_f32 v[178:179], v[154:155], v[178:179], v[162:163]
	v_pk_fma_f32 v[180:181], v[156:157], v[180:181], v[164:165]
	v_pk_mul_f32 v[174:175], v[174:175], s[76:77] op_sel_hi:[1,0]
	v_pk_mul_f32 v[176:177], v[176:177], s[76:77] op_sel_hi:[1,0]
	v_pk_mul_f32 v[178:179], v[178:179], s[76:77] op_sel_hi:[1,0]
	v_pk_mul_f32 v[180:181], v[180:181], s[76:77] op_sel_hi:[1,0]
	v_pk_fma_f32 v[46:47], v[46:47], 0.5, v[174:175] op_sel_hi:[1,0,1]
	v_pk_fma_f32 v[48:49], v[48:49], 0.5, v[176:177] op_sel_hi:[1,0,1]
	v_pk_fma_f32 v[50:51], v[50:51], 0.5, v[178:179] op_sel_hi:[1,0,1]
	v_pk_fma_f32 v[52:53], v[52:53], 0.5, v[180:181] op_sel_hi:[1,0,1]
	v_pk_add_f32 v[174:175], v[46:47], v[50:51]
	v_pk_add_f32 v[176:177], v[48:49], v[52:53]
	v_pk_mul_f32 v[178:179], v[46:47], v[46:47]
	v_pk_mul_f32 v[180:181], v[48:49], v[48:49]
	v_pk_fma_f32 v[178:179], v[50:51], v[50:51], v[178:179]
	v_pk_fma_f32 v[180:181], v[52:53], v[52:53], v[180:181]
	v_pk_add_f32 v[174:175], v[174:175], v[176:177]
	v_pk_add_f32 v[178:179], v[178:179], v[180:181]
	v_cvt_pk_bf16_f32 v102, v46, v47
	v_cvt_pk_bf16_f32 v103, v48, v49
	v_cvt_pk_bf16_f32 v104, v50, v51
	v_cvt_pk_bf16_f32 v105, v52, v53
	v_add_f32_e32 v2, v174, v175
	v_add_f32_e32 v140, v178, v179
	v_lshlrev_b32_e32 v174, 16, v106
	v_and_b32_e32 v175, 0xffff0000, v106
	v_lshlrev_b32_e32 v176, 16, v107
	v_and_b32_e32 v177, 0xffff0000, v107
	v_lshlrev_b32_e32 v178, 16, v108
	v_and_b32_e32 v179, 0xffff0000, v108
	v_lshlrev_b32_e32 v180, 16, v109
	v_and_b32_e32 v181, 0xffff0000, v109
	v_pk_add_f32 v[174:175], v[174:175], v[144:145] op_sel_hi:[1,0] neg_lo:[0,1] neg_hi:[0,1]
	v_pk_add_f32 v[176:177], v[176:177], v[144:145] op_sel_hi:[1,0] neg_lo:[0,1] neg_hi:[0,1]
	v_pk_add_f32 v[178:179], v[178:179], v[144:145] op_sel_hi:[1,0] neg_lo:[0,1] neg_hi:[0,1]
	v_pk_add_f32 v[180:181], v[180:181], v[144:145] op_sel_hi:[1,0] neg_lo:[0,1] neg_hi:[0,1]
	v_pk_mul_f32 v[174:175], v[144:145], v[174:175] op_sel:[1,0] op_sel_hi:[1,1]
	v_pk_mul_f32 v[176:177], v[144:145], v[176:177] op_sel:[1,0] op_sel_hi:[1,1]
	v_pk_mul_f32 v[178:179], v[144:145], v[178:179] op_sel:[1,0] op_sel_hi:[1,1]
	v_pk_mul_f32 v[180:181], v[144:145], v[180:181] op_sel:[1,0] op_sel_hi:[1,1]
	v_pk_fma_f32 v[174:175], v[150:151], v[174:175], v[158:159]
	v_pk_fma_f32 v[176:177], v[152:153], v[176:177], v[160:161]
	v_pk_fma_f32 v[178:179], v[154:155], v[178:179], v[162:163]
	v_pk_fma_f32 v[180:181], v[156:157], v[180:181], v[164:165]
	v_pk_mul_f32 v[174:175], v[174:175], s[76:77] op_sel_hi:[1,0]
	v_pk_mul_f32 v[176:177], v[176:177], s[76:77] op_sel_hi:[1,0]
	v_pk_mul_f32 v[178:179], v[178:179], s[76:77] op_sel_hi:[1,0]
	v_pk_mul_f32 v[180:181], v[180:181], s[76:77] op_sel_hi:[1,0]
	v_pk_fma_f32 v[38:39], v[38:39], 0.5, v[174:175] op_sel_hi:[1,0,1]
	v_pk_fma_f32 v[40:41], v[40:41], 0.5, v[176:177] op_sel_hi:[1,0,1]
	v_pk_fma_f32 v[42:43], v[42:43], 0.5, v[178:179] op_sel_hi:[1,0,1]
	v_pk_fma_f32 v[44:45], v[44:45], 0.5, v[180:181] op_sel_hi:[1,0,1]
	v_pk_add_f32 v[174:175], v[38:39], v[42:43]
	v_pk_add_f32 v[176:177], v[40:41], v[44:45]
	v_pk_mul_f32 v[178:179], v[38:39], v[38:39]
	v_pk_mul_f32 v[180:181], v[40:41], v[40:41]
	v_pk_fma_f32 v[178:179], v[42:43], v[42:43], v[178:179]
	v_pk_fma_f32 v[180:181], v[44:45], v[44:45], v[180:181]
	v_pk_add_f32 v[174:175], v[174:175], v[176:177]
	v_pk_add_f32 v[178:179], v[178:179], v[180:181]
	v_cvt_pk_bf16_f32 v106, v38, v39
	v_cvt_pk_bf16_f32 v107, v40, v41
	v_cvt_pk_bf16_f32 v108, v42, v43
	v_cvt_pk_bf16_f32 v109, v44, v45
	v_add_f32_e32 v4, v174, v175
	v_add_f32_e32 v186, v178, v179
	v_lshlrev_b32_e32 v174, 16, v110
	v_and_b32_e32 v175, 0xffff0000, v110
	v_lshlrev_b32_e32 v176, 16, v111
	v_and_b32_e32 v177, 0xffff0000, v111
	v_lshlrev_b32_e32 v178, 16, v112
	v_and_b32_e32 v179, 0xffff0000, v112
	v_lshlrev_b32_e32 v180, 16, v113
	v_and_b32_e32 v181, 0xffff0000, v113
	v_pk_add_f32 v[174:175], v[174:175], v[146:147] op_sel_hi:[1,0] neg_lo:[0,1] neg_hi:[0,1]
	v_pk_add_f32 v[176:177], v[176:177], v[146:147] op_sel_hi:[1,0] neg_lo:[0,1] neg_hi:[0,1]
	v_pk_add_f32 v[178:179], v[178:179], v[146:147] op_sel_hi:[1,0] neg_lo:[0,1] neg_hi:[0,1]
	v_pk_add_f32 v[180:181], v[180:181], v[146:147] op_sel_hi:[1,0] neg_lo:[0,1] neg_hi:[0,1]
	v_pk_mul_f32 v[174:175], v[146:147], v[174:175] op_sel:[1,0] op_sel_hi:[1,1]
	v_pk_mul_f32 v[176:177], v[146:147], v[176:177] op_sel:[1,0] op_sel_hi:[1,1]
	v_pk_mul_f32 v[178:179], v[146:147], v[178:179] op_sel:[1,0] op_sel_hi:[1,1]
	v_pk_mul_f32 v[180:181], v[146:147], v[180:181] op_sel:[1,0] op_sel_hi:[1,1]
	v_pk_fma_f32 v[174:175], v[150:151], v[174:175], v[158:159]
	v_pk_fma_f32 v[176:177], v[152:153], v[176:177], v[160:161]
	v_pk_fma_f32 v[178:179], v[154:155], v[178:179], v[162:163]
	v_pk_fma_f32 v[180:181], v[156:157], v[180:181], v[164:165]
	v_pk_mul_f32 v[174:175], v[174:175], s[76:77] op_sel_hi:[1,0]
	v_pk_mul_f32 v[176:177], v[176:177], s[76:77] op_sel_hi:[1,0]
	v_pk_mul_f32 v[178:179], v[178:179], s[76:77] op_sel_hi:[1,0]
	v_pk_mul_f32 v[180:181], v[180:181], s[76:77] op_sel_hi:[1,0]
	v_pk_fma_f32 v[30:31], v[30:31], 0.5, v[174:175] op_sel_hi:[1,0,1]
	v_pk_fma_f32 v[32:33], v[32:33], 0.5, v[176:177] op_sel_hi:[1,0,1]
	v_pk_fma_f32 v[34:35], v[34:35], 0.5, v[178:179] op_sel_hi:[1,0,1]
	v_pk_fma_f32 v[36:37], v[36:37], 0.5, v[180:181] op_sel_hi:[1,0,1]
	v_pk_add_f32 v[174:175], v[30:31], v[34:35]
	v_pk_add_f32 v[176:177], v[32:33], v[36:37]
	v_pk_mul_f32 v[178:179], v[30:31], v[30:31]
	v_pk_mul_f32 v[180:181], v[32:33], v[32:33]
	v_pk_fma_f32 v[178:179], v[34:35], v[34:35], v[178:179]
	v_pk_fma_f32 v[180:181], v[36:37], v[36:37], v[180:181]
	v_pk_add_f32 v[174:175], v[174:175], v[176:177]
	v_pk_add_f32 v[178:179], v[178:179], v[180:181]
	v_cvt_pk_bf16_f32 v110, v30, v31
	v_cvt_pk_bf16_f32 v111, v32, v33
	v_cvt_pk_bf16_f32 v112, v34, v35
	v_cvt_pk_bf16_f32 v113, v36, v37
	v_add_f32_e32 v5, v174, v175
	v_add_f32_e32 v187, v178, v179
	v_lshlrev_b32_e32 v174, 16, v114
	v_and_b32_e32 v175, 0xffff0000, v114
	v_lshlrev_b32_e32 v176, 16, v115
	v_and_b32_e32 v177, 0xffff0000, v115
	v_lshlrev_b32_e32 v178, 16, v116
	v_and_b32_e32 v179, 0xffff0000, v116
	v_lshlrev_b32_e32 v180, 16, v117
	v_and_b32_e32 v181, 0xffff0000, v117
	v_pk_add_f32 v[174:175], v[174:175], v[148:149] op_sel_hi:[1,0] neg_lo:[0,1] neg_hi:[0,1]
	v_pk_add_f32 v[176:177], v[176:177], v[148:149] op_sel_hi:[1,0] neg_lo:[0,1] neg_hi:[0,1]
	v_pk_add_f32 v[178:179], v[178:179], v[148:149] op_sel_hi:[1,0] neg_lo:[0,1] neg_hi:[0,1]
	v_pk_add_f32 v[180:181], v[180:181], v[148:149] op_sel_hi:[1,0] neg_lo:[0,1] neg_hi:[0,1]
	v_pk_mul_f32 v[174:175], v[148:149], v[174:175] op_sel:[1,0] op_sel_hi:[1,1]
	v_pk_mul_f32 v[176:177], v[148:149], v[176:177] op_sel:[1,0] op_sel_hi:[1,1]
	v_pk_mul_f32 v[178:179], v[148:149], v[178:179] op_sel:[1,0] op_sel_hi:[1,1]
	v_pk_mul_f32 v[180:181], v[148:149], v[180:181] op_sel:[1,0] op_sel_hi:[1,1]
	v_pk_fma_f32 v[174:175], v[150:151], v[174:175], v[158:159]
	v_pk_fma_f32 v[176:177], v[152:153], v[176:177], v[160:161]
	v_pk_fma_f32 v[178:179], v[154:155], v[178:179], v[162:163]
	v_pk_fma_f32 v[180:181], v[156:157], v[180:181], v[164:165]
	v_pk_mul_f32 v[174:175], v[174:175], s[76:77] op_sel_hi:[1,0]
	v_pk_mul_f32 v[176:177], v[176:177], s[76:77] op_sel_hi:[1,0]
	v_pk_mul_f32 v[178:179], v[178:179], s[76:77] op_sel_hi:[1,0]
	v_pk_mul_f32 v[180:181], v[180:181], s[76:77] op_sel_hi:[1,0]
	v_pk_fma_f32 v[22:23], v[22:23], 0.5, v[174:175] op_sel_hi:[1,0,1]
	v_pk_fma_f32 v[24:25], v[24:25], 0.5, v[176:177] op_sel_hi:[1,0,1]
	v_pk_fma_f32 v[26:27], v[26:27], 0.5, v[178:179] op_sel_hi:[1,0,1]
	v_pk_fma_f32 v[28:29], v[28:29], 0.5, v[180:181] op_sel_hi:[1,0,1]
	v_pk_add_f32 v[174:175], v[22:23], v[26:27]
	v_pk_add_f32 v[176:177], v[24:25], v[28:29]
	v_pk_mul_f32 v[178:179], v[22:23], v[22:23]
	v_pk_mul_f32 v[180:181], v[24:25], v[24:25]
	v_pk_fma_f32 v[178:179], v[26:27], v[26:27], v[178:179]
	v_pk_fma_f32 v[180:181], v[28:29], v[28:29], v[180:181]
	v_pk_add_f32 v[174:175], v[174:175], v[176:177]
	v_pk_add_f32 v[178:179], v[178:179], v[180:181]
	v_cvt_pk_bf16_f32 v114, v22, v23
	v_cvt_pk_bf16_f32 v115, v24, v25
	v_cvt_pk_bf16_f32 v116, v26, v27
	v_cvt_pk_bf16_f32 v117, v28, v29
	v_add_f32_e32 v139, v174, v175
	v_add_f32_e32 v197, v178, v179
	global_store_dwordx4 v135, v[102:105], s[18:19]
	global_store_dwordx4 v135, v[106:109], s[6:7]
	global_store_dwordx4 v135, v[110:113], s[8:9]
	global_store_dwordx4 v135, v[114:117], s[10:11]
	ds_read_b128 v[150:153], v137 offset:512
	ds_read_b128 v[154:157], v137 offset:528
	ds_read_b128 v[158:161], v137 offset:1536
	ds_read_b128 v[162:165], v137 offset:1552
	s_waitcnt lgkmcnt(0)
	s_waitcnt vmcnt(14)
	v_lshlrev_b32_e32 v174, 16, v118
	v_and_b32_e32 v175, 0xffff0000, v118
	v_lshlrev_b32_e32 v176, 16, v119
	v_and_b32_e32 v177, 0xffff0000, v119
	v_lshlrev_b32_e32 v178, 16, v120
	v_and_b32_e32 v179, 0xffff0000, v120
	v_lshlrev_b32_e32 v180, 16, v121
	v_and_b32_e32 v181, 0xffff0000, v121
	v_pk_add_f32 v[174:175], v[174:175], v[142:143] op_sel_hi:[1,0] neg_lo:[0,1] neg_hi:[0,1]
	v_pk_add_f32 v[176:177], v[176:177], v[142:143] op_sel_hi:[1,0] neg_lo:[0,1] neg_hi:[0,1]
	v_pk_add_f32 v[178:179], v[178:179], v[142:143] op_sel_hi:[1,0] neg_lo:[0,1] neg_hi:[0,1]
	v_pk_add_f32 v[180:181], v[180:181], v[142:143] op_sel_hi:[1,0] neg_lo:[0,1] neg_hi:[0,1]
	v_pk_mul_f32 v[174:175], v[142:143], v[174:175] op_sel:[1,0] op_sel_hi:[1,1]
	v_pk_mul_f32 v[176:177], v[142:143], v[176:177] op_sel:[1,0] op_sel_hi:[1,1]
	v_pk_mul_f32 v[178:179], v[142:143], v[178:179] op_sel:[1,0] op_sel_hi:[1,1]
	v_pk_mul_f32 v[180:181], v[142:143], v[180:181] op_sel:[1,0] op_sel_hi:[1,1]
	v_pk_fma_f32 v[174:175], v[150:151], v[174:175], v[158:159]
	v_pk_fma_f32 v[176:177], v[152:153], v[176:177], v[160:161]
	v_pk_fma_f32 v[178:179], v[154:155], v[178:179], v[162:163]
	v_pk_fma_f32 v[180:181], v[156:157], v[180:181], v[164:165]
	v_pk_mul_f32 v[174:175], v[174:175], s[76:77] op_sel_hi:[1,0]
	v_pk_mul_f32 v[176:177], v[176:177], s[76:77] op_sel_hi:[1,0]
	v_pk_mul_f32 v[178:179], v[178:179], s[76:77] op_sel_hi:[1,0]
	v_pk_mul_f32 v[180:181], v[180:181], s[76:77] op_sel_hi:[1,0]
	v_pk_fma_f32 v[14:15], v[14:15], 0.5, v[174:175] op_sel_hi:[1,0,1]
	v_pk_fma_f32 v[16:17], v[16:17], 0.5, v[176:177] op_sel_hi:[1,0,1]
	v_pk_fma_f32 v[18:19], v[18:19], 0.5, v[178:179] op_sel_hi:[1,0,1]
	v_pk_fma_f32 v[20:21], v[20:21], 0.5, v[180:181] op_sel_hi:[1,0,1]
	v_pk_add_f32 v[174:175], v[14:15], v[18:19]
	v_pk_add_f32 v[176:177], v[16:17], v[20:21]
	v_pk_mul_f32 v[178:179], v[14:15], v[14:15]
	v_pk_mul_f32 v[180:181], v[16:17], v[16:17]
	v_pk_fma_f32 v[178:179], v[18:19], v[18:19], v[178:179]
	v_pk_fma_f32 v[180:181], v[20:21], v[20:21], v[180:181]
	v_pk_add_f32 v[174:175], v[174:175], v[176:177]
	v_pk_add_f32 v[178:179], v[178:179], v[180:181]
	v_cvt_pk_bf16_f32 v118, v14, v15
	v_cvt_pk_bf16_f32 v119, v16, v17
	v_cvt_pk_bf16_f32 v120, v18, v19
	v_cvt_pk_bf16_f32 v121, v20, v21
	v_add_f32_e32 v174, v174, v175
	v_add_f32_e32 v178, v178, v179
	v_add_f32_e32 v2, v2, v174
	v_add_f32_e32 v140, v140, v178
	v_lshlrev_b32_e32 v174, 16, v122
	v_and_b32_e32 v175, 0xffff0000, v122
	v_lshlrev_b32_e32 v176, 16, v123
	v_and_b32_e32 v177, 0xffff0000, v123
	v_lshlrev_b32_e32 v178, 16, v124
	v_and_b32_e32 v179, 0xffff0000, v124
	v_lshlrev_b32_e32 v180, 16, v125
	v_and_b32_e32 v181, 0xffff0000, v125
	v_pk_add_f32 v[174:175], v[174:175], v[144:145] op_sel_hi:[1,0] neg_lo:[0,1] neg_hi:[0,1]
	v_pk_add_f32 v[176:177], v[176:177], v[144:145] op_sel_hi:[1,0] neg_lo:[0,1] neg_hi:[0,1]
	v_pk_add_f32 v[178:179], v[178:179], v[144:145] op_sel_hi:[1,0] neg_lo:[0,1] neg_hi:[0,1]
	v_pk_add_f32 v[180:181], v[180:181], v[144:145] op_sel_hi:[1,0] neg_lo:[0,1] neg_hi:[0,1]
	v_pk_mul_f32 v[174:175], v[144:145], v[174:175] op_sel:[1,0] op_sel_hi:[1,1]
	v_pk_mul_f32 v[176:177], v[144:145], v[176:177] op_sel:[1,0] op_sel_hi:[1,1]
	v_pk_mul_f32 v[178:179], v[144:145], v[178:179] op_sel:[1,0] op_sel_hi:[1,1]
	v_pk_mul_f32 v[180:181], v[144:145], v[180:181] op_sel:[1,0] op_sel_hi:[1,1]
	v_pk_fma_f32 v[174:175], v[150:151], v[174:175], v[158:159]
	v_pk_fma_f32 v[176:177], v[152:153], v[176:177], v[160:161]
	v_pk_fma_f32 v[178:179], v[154:155], v[178:179], v[162:163]
	v_pk_fma_f32 v[180:181], v[156:157], v[180:181], v[164:165]
	v_pk_mul_f32 v[174:175], v[174:175], s[76:77] op_sel_hi:[1,0]
	v_pk_mul_f32 v[176:177], v[176:177], s[76:77] op_sel_hi:[1,0]
	v_pk_mul_f32 v[178:179], v[178:179], s[76:77] op_sel_hi:[1,0]
	v_pk_mul_f32 v[180:181], v[180:181], s[76:77] op_sel_hi:[1,0]
	v_pk_fma_f32 v[6:7], v[6:7], 0.5, v[174:175] op_sel_hi:[1,0,1]
	v_pk_fma_f32 v[8:9], v[8:9], 0.5, v[176:177] op_sel_hi:[1,0,1]
	v_pk_fma_f32 v[10:11], v[10:11], 0.5, v[178:179] op_sel_hi:[1,0,1]
	v_pk_fma_f32 v[12:13], v[12:13], 0.5, v[180:181] op_sel_hi:[1,0,1]
	v_pk_add_f32 v[174:175], v[6:7], v[10:11]
	v_pk_add_f32 v[176:177], v[8:9], v[12:13]
	v_pk_mul_f32 v[178:179], v[6:7], v[6:7]
	v_pk_mul_f32 v[180:181], v[8:9], v[8:9]
	v_pk_fma_f32 v[178:179], v[10:11], v[10:11], v[178:179]
	v_pk_fma_f32 v[180:181], v[12:13], v[12:13], v[180:181]
	v_pk_add_f32 v[174:175], v[174:175], v[176:177]
	v_pk_add_f32 v[178:179], v[178:179], v[180:181]
	v_cvt_pk_bf16_f32 v122, v6, v7
	v_cvt_pk_bf16_f32 v123, v8, v9
	v_cvt_pk_bf16_f32 v124, v10, v11
	v_cvt_pk_bf16_f32 v125, v12, v13
	v_add_f32_e32 v174, v174, v175
	v_add_f32_e32 v178, v178, v179
	v_add_f32_e32 v4, v4, v174
	v_add_f32_e32 v186, v186, v178
	v_lshlrev_b32_e32 v174, 16, v126
	v_and_b32_e32 v175, 0xffff0000, v126
	v_lshlrev_b32_e32 v176, 16, v127
	v_and_b32_e32 v177, 0xffff0000, v127
	v_lshlrev_b32_e32 v178, 16, v128
	v_and_b32_e32 v179, 0xffff0000, v128
	v_lshlrev_b32_e32 v180, 16, v129
	v_and_b32_e32 v181, 0xffff0000, v129
	v_pk_add_f32 v[174:175], v[174:175], v[146:147] op_sel_hi:[1,0] neg_lo:[0,1] neg_hi:[0,1]
	v_pk_add_f32 v[176:177], v[176:177], v[146:147] op_sel_hi:[1,0] neg_lo:[0,1] neg_hi:[0,1]
	v_pk_add_f32 v[178:179], v[178:179], v[146:147] op_sel_hi:[1,0] neg_lo:[0,1] neg_hi:[0,1]
	v_pk_add_f32 v[180:181], v[180:181], v[146:147] op_sel_hi:[1,0] neg_lo:[0,1] neg_hi:[0,1]
	v_pk_mul_f32 v[174:175], v[146:147], v[174:175] op_sel:[1,0] op_sel_hi:[1,1]
	v_pk_mul_f32 v[176:177], v[146:147], v[176:177] op_sel:[1,0] op_sel_hi:[1,1]
	v_pk_mul_f32 v[178:179], v[146:147], v[178:179] op_sel:[1,0] op_sel_hi:[1,1]
	v_pk_mul_f32 v[180:181], v[146:147], v[180:181] op_sel:[1,0] op_sel_hi:[1,1]
	v_pk_fma_f32 v[174:175], v[150:151], v[174:175], v[158:159]
	v_pk_fma_f32 v[176:177], v[152:153], v[176:177], v[160:161]
	v_pk_fma_f32 v[178:179], v[154:155], v[178:179], v[162:163]
	v_pk_fma_f32 v[180:181], v[156:157], v[180:181], v[164:165]
	v_pk_mul_f32 v[174:175], v[174:175], s[76:77] op_sel_hi:[1,0]
	v_pk_mul_f32 v[176:177], v[176:177], s[76:77] op_sel_hi:[1,0]
	v_pk_mul_f32 v[178:179], v[178:179], s[76:77] op_sel_hi:[1,0]
	v_pk_mul_f32 v[180:181], v[180:181], s[76:77] op_sel_hi:[1,0]
	v_pk_fma_f32 v[54:55], v[54:55], 0.5, v[174:175] op_sel_hi:[1,0,1]
	v_pk_fma_f32 v[56:57], v[56:57], 0.5, v[176:177] op_sel_hi:[1,0,1]
	v_pk_fma_f32 v[62:63], v[62:63], 0.5, v[178:179] op_sel_hi:[1,0,1]
	v_pk_fma_f32 v[64:65], v[64:65], 0.5, v[180:181] op_sel_hi:[1,0,1]
	v_pk_add_f32 v[174:175], v[54:55], v[62:63]
	v_pk_add_f32 v[176:177], v[56:57], v[64:65]
	v_pk_mul_f32 v[178:179], v[54:55], v[54:55]
	v_pk_mul_f32 v[180:181], v[56:57], v[56:57]
	v_pk_fma_f32 v[178:179], v[62:63], v[62:63], v[178:179]
	v_pk_fma_f32 v[180:181], v[64:65], v[64:65], v[180:181]
	v_pk_add_f32 v[174:175], v[174:175], v[176:177]
	v_pk_add_f32 v[178:179], v[178:179], v[180:181]
	v_cvt_pk_bf16_f32 v126, v54, v55
	v_cvt_pk_bf16_f32 v127, v56, v57
	v_cvt_pk_bf16_f32 v128, v62, v63
	v_cvt_pk_bf16_f32 v129, v64, v65
	v_add_f32_e32 v174, v174, v175
	v_add_f32_e32 v178, v178, v179
	v_add_f32_e32 v5, v5, v174
	v_add_f32_e32 v187, v187, v178
	v_lshlrev_b32_e32 v174, 16, v130
	v_and_b32_e32 v175, 0xffff0000, v130
	v_lshlrev_b32_e32 v176, 16, v131
	v_and_b32_e32 v177, 0xffff0000, v131
	v_lshlrev_b32_e32 v178, 16, v132
	v_and_b32_e32 v179, 0xffff0000, v132
	v_lshlrev_b32_e32 v180, 16, v133
	v_and_b32_e32 v181, 0xffff0000, v133
	v_pk_add_f32 v[174:175], v[174:175], v[148:149] op_sel_hi:[1,0] neg_lo:[0,1] neg_hi:[0,1]
	v_pk_add_f32 v[176:177], v[176:177], v[148:149] op_sel_hi:[1,0] neg_lo:[0,1] neg_hi:[0,1]
	v_pk_add_f32 v[178:179], v[178:179], v[148:149] op_sel_hi:[1,0] neg_lo:[0,1] neg_hi:[0,1]
	v_pk_add_f32 v[180:181], v[180:181], v[148:149] op_sel_hi:[1,0] neg_lo:[0,1] neg_hi:[0,1]
	v_pk_mul_f32 v[174:175], v[148:149], v[174:175] op_sel:[1,0] op_sel_hi:[1,1]
	v_pk_mul_f32 v[176:177], v[148:149], v[176:177] op_sel:[1,0] op_sel_hi:[1,1]
	v_pk_mul_f32 v[178:179], v[148:149], v[178:179] op_sel:[1,0] op_sel_hi:[1,1]
	v_pk_mul_f32 v[180:181], v[148:149], v[180:181] op_sel:[1,0] op_sel_hi:[1,1]
	v_pk_fma_f32 v[174:175], v[150:151], v[174:175], v[158:159]
	v_pk_fma_f32 v[176:177], v[152:153], v[176:177], v[160:161]
	v_pk_fma_f32 v[178:179], v[154:155], v[178:179], v[162:163]
	v_pk_fma_f32 v[180:181], v[156:157], v[180:181], v[164:165]
	v_pk_mul_f32 v[174:175], v[174:175], s[76:77] op_sel_hi:[1,0]
	v_pk_mul_f32 v[176:177], v[176:177], s[76:77] op_sel_hi:[1,0]
	v_pk_mul_f32 v[178:179], v[178:179], s[76:77] op_sel_hi:[1,0]
	v_pk_mul_f32 v[180:181], v[180:181], s[76:77] op_sel_hi:[1,0]
	v_pk_fma_f32 v[58:59], v[58:59], 0.5, v[174:175] op_sel_hi:[1,0,1]
	v_pk_fma_f32 v[60:61], v[60:61], 0.5, v[176:177] op_sel_hi:[1,0,1]
	v_pk_fma_f32 v[66:67], v[66:67], 0.5, v[178:179] op_sel_hi:[1,0,1]
	v_pk_fma_f32 v[68:69], v[68:69], 0.5, v[180:181] op_sel_hi:[1,0,1]
	v_pk_add_f32 v[174:175], v[58:59], v[66:67]
	v_pk_add_f32 v[176:177], v[60:61], v[68:69]
	v_pk_mul_f32 v[178:179], v[58:59], v[58:59]
	v_pk_mul_f32 v[180:181], v[60:61], v[60:61]
	v_pk_fma_f32 v[178:179], v[66:67], v[66:67], v[178:179]
	v_pk_fma_f32 v[180:181], v[68:69], v[68:69], v[180:181]
	v_pk_add_f32 v[174:175], v[174:175], v[176:177]
	v_pk_add_f32 v[178:179], v[178:179], v[180:181]
	v_cvt_pk_bf16_f32 v130, v58, v59
	v_cvt_pk_bf16_f32 v131, v60, v61
	v_cvt_pk_bf16_f32 v132, v66, v67
	v_cvt_pk_bf16_f32 v133, v68, v69
	v_add_f32_e32 v174, v174, v175
	v_add_f32_e32 v178, v178, v179
	v_add_f32_e32 v139, v139, v174
	v_add_f32_e32 v197, v197, v178
	global_store_dwordx4 v135, v[118:121], s[18:19] offset:256
	global_store_dwordx4 v135, v[122:125], s[6:7] offset:256
	global_store_dwordx4 v135, v[126:129], s[8:9] offset:256
	global_store_dwordx4 v135, v[130:133], s[10:11] offset:256
	ds_bpermute_b32 v174, v201, v2
	ds_bpermute_b32 v175, v201, v4
	ds_bpermute_b32 v176, v201, v5
	ds_bpermute_b32 v177, v201, v139
	ds_bpermute_b32 v178, v201, v140
	ds_bpermute_b32 v179, v201, v186
	ds_bpermute_b32 v180, v201, v187
	ds_bpermute_b32 v181, v201, v197
	s_waitcnt lgkmcnt(0)
	v_add_f32_e32 v2, v2, v174
	v_add_f32_e32 v4, v4, v175
	v_add_f32_e32 v5, v5, v176
	v_add_f32_e32 v139, v139, v177
	v_add_f32_e32 v140, v140, v178
	v_add_f32_e32 v186, v186, v179
	v_add_f32_e32 v187, v187, v180
	v_add_f32_e32 v197, v197, v181
	ds_bpermute_b32 v174, v203, v2
	ds_bpermute_b32 v175, v203, v4
	ds_bpermute_b32 v176, v203, v5
	ds_bpermute_b32 v177, v203, v139
	ds_bpermute_b32 v178, v203, v140
	ds_bpermute_b32 v179, v203, v186
	ds_bpermute_b32 v180, v203, v187
	ds_bpermute_b32 v181, v203, v197
	s_waitcnt lgkmcnt(0)
	v_add_f32_e32 v2, v2, v174
	v_add_f32_e32 v4, v4, v175
	v_add_f32_e32 v5, v5, v176
	v_add_f32_e32 v139, v139, v177
	v_add_f32_e32 v140, v140, v178
	v_add_f32_e32 v186, v186, v179
	v_add_f32_e32 v187, v187, v180
	v_add_f32_e32 v197, v197, v181
	v_cmp_eq_u32_e32 vcc, 1, v191
	s_nop 1
	v_cndmask_b32_e32 v2, v2, v4, vcc
	v_cndmask_b32_e32 v140, v140, v186, vcc
	v_cmp_eq_u32_e32 vcc, 2, v191
	s_nop 1
	v_cndmask_b32_e32 v2, v2, v5, vcc
	v_cndmask_b32_e32 v140, v140, v187, vcc
	v_cmp_eq_u32_e32 vcc, 3, v191
	s_nop 1
	v_cndmask_b32_e32 v2, v2, v139, vcc
	v_cndmask_b32_e32 v140, v140, v197, vcc
	global_atomic_add_f32 v138, v2, s[16:17] offset:1024
	global_atomic_add_f32 v138, v140, s[16:17] offset:1028
	s_branch .LBB0_1106
.Ltramp_gbar:
	s_branch .LBB0_1633
.LBB0_1027:
	v_pk_fma_f32 v[174:175], v[148:149], v[158:159], v[96:97] op_sel_hi:[0,1,1] neg_lo:[1,0,0] neg_hi:[1,0,0]
	v_pk_fma_f32 v[178:179], v[154:155], v[174:175], v[146:147] op_sel_hi:[1,1,0]
	v_pk_fma_f32 v[174:175], v[148:149], v[164:165], v[100:101] op_sel_hi:[0,1,1] neg_lo:[1,0,0] neg_hi:[1,0,0]
	v_pk_fma_f32 v[176:177], v[148:149], v[150:151], v[94:95] op_sel_hi:[0,1,1] neg_lo:[1,0,0] neg_hi:[1,0,0]
	v_pk_fma_f32 v[180:181], v[148:149], v[156:157], v[98:99] op_sel_hi:[0,1,1] neg_lo:[1,0,0] neg_hi:[1,0,0]
	v_pk_fma_f32 v[182:183], v[162:163], v[174:175], v[146:147] op_sel_hi:[1,1,0]
	v_cvt_pk_bf16_f32 v175, v178, v179
	v_mov_b64_e32 v[178:179], s[6:7]
	s_movk_i32 s8, 0x4800
	v_pk_fma_f32 v[176:177], v[152:153], v[176:177], v[146:147] op_sel_hi:[1,1,0]
	v_pk_fma_f32 v[180:181], v[160:161], v[180:181], v[146:147] op_sel_hi:[1,1,0]
	v_mad_i64_i32 v[178:179], s[8:9], v2, s8, v[178:179]
	v_cvt_pk_bf16_f32 v174, v176, v177
	v_cvt_pk_bf16_f32 v176, v180, v181
	v_cvt_pk_bf16_f32 v177, v182, v183
	v_lshl_add_u64 v[178:179], v[4:5], 1, v[178:179]
	global_store_dwordx4 v[178:179], v[174:177], off offset:256
	s_andn2_b64 vcc, exec, s[10:11]
	s_cbranch_vccnz .LBB0_985

.LBB0_1661:
	s_cmp_lt_u32 s2, 0x100001
	s_mov_b64 s[24:25], 0
	s_cselect_b64 s[26:27], -1, 0
	s_and_b64 vcc, exec, s[26:27]
	s_cbranch_vccz .LBB0_1655
	s_branch .LBB0_1660
.LBB0_1665:
	s_or_b64 exec, exec, s[18:19]
	s_xor_b64 s[2:3], s[20:21], -1
	s_and_saveexec_b64 s[16:17], s[2:3]
	s_xor_b64 s[16:17], exec, s[16:17]
	s_cbranch_execz .LBB0_1668
	s_mov_b64 s[16:17], exec
	v_mbcnt_lo_u32_b32 v2, s16, 0
	v_mbcnt_hi_u32_b32 v2, s17, v2
	v_cmp_eq_u32_e32 vcc, 0, v2
	s_and_b64 s[2:3], exec, vcc
	s_mov_b64 exec, s[2:3]
	s_cbranch_execz .LBB0_1668
	s_bcnt1_i32_b64 s2, s[16:17]
	v_mov_b32_e32 v2, s2
	global_atomic_add v3, v2, s[14:15]
